# v104 + barrier #0 issues its returning arrival atomic together with the census reads (round trips overlap)
# baseline (speedup 1.0000x reference)
; #define LAS __attribute__((address_space(3)))
; __device__ __forceinline__ unsigned xb_add(unsigned* p, unsigned v) { return __hip_atomic_fetch_add(p, v, __ATOMIC_RELAXED, __HIP_MEMORY_SCOPE_AGENT); }
; __device__ __forceinline__ unsigned xb_xcc_id() { return (unsigned)__builtin_amdgcn_s_getreg((3 << 11) | 20) & 0xFu; }
; __device__ __forceinline__ XcdBarrier xcd_barrier_post(unsigned* bar, volatile LAS unsigned* st) {
;     XcdBarrier b; b.bar = bar; b.x = xb_xcc_id(); b.st = st;
;     if (threadIdx.x == 0) (void)xb_add(&bar[XB_XCNT(b.x)], 1u);
;     return b;
; __device__ __forceinline__ void xcd_barrier(const XcdBarrier& b) {
;     ...
;         const unsigned old = xb_add(&bar[XB_XSUB(b.x)], 1u);
.Lgb0_tag_ok:
	v_readlane_b32 s3, v252, 5
	s_lshl_b32 s8, s3, 8
	v_mov_b32_e32 v1, 1
	v_mov_b32_e32 v4, s8
	global_atomic_add v4, v1, s[84:85] offset:1024
	s_add_i32 s14, s8, 0x1000
	v_mov_b32_e32 v24, s14
	global_atomic_add v25, v24, v1, s[84:85] offset:1024 sc0
	v_mov_b32_e32 v5, 0x1000

; __device__ __forceinline__ unsigned xb_ld(unsigned* p)              { return __hip_atomic_load(p, __ATOMIC_RELAXED, __HIP_MEMORY_SCOPE_AGENT); }
; __device__ __forceinline__ unsigned xb_add(unsigned* p, unsigned v) { return __hip_atomic_fetch_add(p, v, __ATOMIC_RELAXED, __HIP_MEMORY_SCOPE_AGENT); }
; #define XB_SPIN(cond, bar) do { unsigned _sp = 0; while (cond) { __builtin_amdgcn_s_sleep(1); \
;     if ((++_sp & 255u) == 0u) { if (xb_ld(&(bar)[XB_TMO])) break; if (_sp > XB_SPIN_CAP) { atomicAdd(&(bar)[XB_TMO], 1u); break; } } } } while (0)
; __device__ __forceinline__ void xcd_barrier_complete(unsigned* bar, unsigned x, unsigned& nloc, unsigned& nx) {
;     ...
;     nloc = mine > 0u ? mine : 1u; nx = cnt > 0u ? cnt : 1u;
; }
; __device__ __forceinline__ void xcd_barrier(const XcdBarrier& b) {
;     asm volatile("s_waitcnt vmcnt(0)" ::: "memory");
;     __syncthreads();
;     if (threadIdx.x == 0) {
;         unsigned* bar = b.bar;
;         __builtin_amdgcn_s_waitcnt(0);
;         unsigned nloc = b.st[0], nx = b.st[1];
;         if (nloc == 0u) { xcd_barrier_complete(bar, b.x, nloc, nx); b.st[0] = nloc; b.st[1] = nx; }
;         const unsigned old = xb_add(&bar[XB_XSUB(b.x)], 1u);
;         const unsigned gen = old / nloc;
;         if (old + 1u == (gen + 1u) * nloc) {
;             __builtin_amdgcn_fence(__ATOMIC_RELEASE, "agent");
;             asm volatile("s_waitcnt vmcnt(0)" ::: "memory");
;             const unsigned og = xb_add(&bar[XB_TOP], 1u);
;             const unsigned tg = og / nx;
;             if (og + 1u == (tg + 1u) * nx) xb_add(&bar[XB_TOPGEN], 1u);
;             else XB_SPIN(xb_ld(&bar[XB_TOPGEN]) == tg, bar);
;             __builtin_amdgcn_fence(__ATOMIC_ACQUIRE, "agent");
;             xb_add(&bar[XB_XGEN(b.x)], 1u);
.Lgb0_census_ok:
	s_max_u32 s11, s11, 1
	s_max_u32 s10, s10, 1
	v_mov_b32_e32 v6, 0x23fc0
	v_mov_b32_e32 v7, s11
	ds_write_b32 v6, v7
	v_mov_b32_e32 v7, s10
	ds_write_b32 v6, v7 offset:4
	v_readfirstlane_b32 s6, v25
	s_add_i32 s6, s6, 1
	s_cmp_eq_u32 s6, s11
	s_cbranch_scc0 .Lgb0_poll
	buffer_wbl2 sc1
	s_waitcnt vmcnt(0)
	v_mov_b32_e32 v4, 0x3000
	global_atomic_add v6, v4, v1, s[84:85] offset:1024 sc0
	s_waitcnt vmcnt(0)
	v_readfirstlane_b32 s6, v6
	s_add_i32 s6, s6, 1
	v_mov_b32_e32 v4, 0x3100
	s_cmp_eq_u32 s6, s10
	s_cbranch_scc0 .Lgb0_lpoll
	global_atomic_add v4, v1, s[84:85] offset:1024
	s_branch .Lgb0_lout
